# G4 K-loop last trip: plain loads touch the residual tile's lines so the epilogue's reads hit L2
# speedup vs baseline: 1.0014x; 1.0014x over previous
.LBB0_1044:
	s_add_u32 s14, s38, 0x100
	s_addc_u32 s15, s39, 0
	s_add_i32 s24, 0, 0x10000
	s_cmp_eq_u32 s61, 40
	s_cselect_b32 s45, s13, s15
	s_cselect_b32 s44, s12, s14
	v_add_u32_e32 v144, s24, v147
	s_cselect_b32 s43, s29, s60
	s_cselect_b32 s42, s28, s55
	s_cmp_lg_u32 s61, 40
	s_cbranch_scc1 .Ltouch_g4_skip
	v_lshrrev_b32_e32 v249, 2, v194
	v_lshlrev_b32_e32 v249, 11, v249
	v_and_b32_e32 v248, 3, v194
	v_lshl_add_u32 v249, v248, 7, v249
	s_lshl_b32 s100, s54, 19
	s_lshl_b32 s101, s51, 9
	s_add_u32 s100, s100, s101
	s_add_u32 s100, s6, s100
	s_addc_u32 s101, s7, 0
	s_nop 0
	global_load_dword v248, v249, s[100:101]
	s_add_u32 s100, s100, 0x40000
	s_addc_u32 s101, s101, 0
	s_nop 0
	global_load_dword v248, v249, s[100:101]
.Ltouch_g4_skip:
	s_add_i32 s25, 0, 0x14000
	ds_read_b128 v[140:143], v144
	ds_read_b128 v[150:153], v144 offset:1024
	ds_read_b128 v[172:175], v144 offset:2048
	ds_read_b128 v[176:179], v144 offset:3072
	v_add_u32_e32 v144, s25, v147
	ds_read_b128 v[180:183], v144
	ds_read_b128 v[184:187], v144 offset:1024
	ds_read_b128 v[188:191], v144 offset:2048
	ds_read_b128 v[200:203], v144 offset:3072
	v_lshl_add_u64 v[144:145], s[38:39], 0, v[138:139]
	s_add_i32 m0, s21, 0xc000
	ds_read_b128 v[204:207], v149
	ds_read_b128 v[208:211], v149 offset:1024
	ds_read_b128 v[212:215], v149 offset:2048
	ds_read_b128 v[216:219], v149 offset:3072
	ds_read_b128 v[220:223], v149 offset:4096
	ds_read_b128 v[224:227], v149 offset:5120
	ds_read_b128 v[228:231], v149 offset:6144
	ds_read_b128 v[232:235], v149 offset:7168
	global_load_lds_dwordx4 v[144:145], off
	v_lshl_add_u64 v[144:145], s[38:39], 0, v[136:137]
	s_add_i32 m0, s21, 0xe000
	s_nop 0
	global_load_lds_dwordx4 v[144:145], off
	s_waitcnt vmcnt(8)
	s_waitcnt lgkmcnt(0)
	s_barrier
	s_setprio 1
	s_waitcnt lgkmcnt(0)
	v_mfma_f32_16x16x32_bf16 v[128:131], v[140:143], v[204:207], v[128:131]
	v_mfma_f32_16x16x32_bf16 v[124:127], v[172:175], v[204:207], v[124:127]
	v_mfma_f32_16x16x32_bf16 v[112:115], v[140:143], v[212:215], v[112:115]
	v_mfma_f32_16x16x32_bf16 v[108:111], v[172:175], v[212:215], v[108:111]
	v_mfma_f32_16x16x32_bf16 v[96:99], v[140:143], v[220:223], v[96:99]
	v_mfma_f32_16x16x32_bf16 v[92:95], v[172:175], v[220:223], v[92:95]
	v_mfma_f32_16x16x32_bf16 v[80:83], v[140:143], v[228:231], v[80:83]
	v_mfma_f32_16x16x32_bf16 v[76:79], v[172:175], v[228:231], v[76:79]
	v_mfma_f32_16x16x32_bf16 v[128:131], v[150:153], v[208:211], v[128:131]
	v_mfma_f32_16x16x32_bf16 v[124:127], v[176:179], v[208:211], v[124:127]
	v_mfma_f32_16x16x32_bf16 v[112:115], v[150:153], v[216:219], v[112:115]
	v_mfma_f32_16x16x32_bf16 v[108:111], v[176:179], v[216:219], v[108:111]
	v_mfma_f32_16x16x32_bf16 v[96:99], v[150:153], v[224:227], v[96:99]
	v_mfma_f32_16x16x32_bf16 v[92:95], v[176:179], v[224:227], v[92:95]
	v_mfma_f32_16x16x32_bf16 v[80:83], v[150:153], v[232:235], v[80:83]
	v_mfma_f32_16x16x32_bf16 v[76:79], v[176:179], v[232:235], v[76:79]
	s_setprio 0
	s_setprio 1
	v_mfma_f32_16x16x32_bf16 v[120:123], v[180:183], v[204:207], v[120:123]
	v_mfma_f32_16x16x32_bf16 v[116:119], v[188:191], v[204:207], v[116:119]
	v_mfma_f32_16x16x32_bf16 v[104:107], v[180:183], v[212:215], v[104:107]
	v_mfma_f32_16x16x32_bf16 v[100:103], v[188:191], v[212:215], v[100:103]
	v_mfma_f32_16x16x32_bf16 v[88:91], v[180:183], v[220:223], v[88:91]
	v_mfma_f32_16x16x32_bf16 v[84:87], v[188:191], v[220:223], v[84:87]
	v_mfma_f32_16x16x32_bf16 v[72:75], v[180:183], v[228:231], v[72:75]
	v_mfma_f32_16x16x32_bf16 v[68:71], v[188:191], v[228:231], v[68:71]
	v_mfma_f32_16x16x32_bf16 v[120:123], v[184:187], v[208:211], v[120:123]
	v_mfma_f32_16x16x32_bf16 v[116:119], v[200:203], v[208:211], v[116:119]
	v_mfma_f32_16x16x32_bf16 v[104:107], v[184:187], v[216:219], v[104:107]
	v_mfma_f32_16x16x32_bf16 v[100:103], v[200:203], v[216:219], v[100:103]
	v_mfma_f32_16x16x32_bf16 v[88:91], v[184:187], v[224:227], v[88:91]
	v_mfma_f32_16x16x32_bf16 v[84:87], v[200:203], v[224:227], v[84:87]
	v_mfma_f32_16x16x32_bf16 v[72:75], v[184:187], v[232:235], v[72:75]
	v_mfma_f32_16x16x32_bf16 v[68:71], v[200:203], v[232:235], v[68:71]
	s_setprio 0
	s_barrier
	s_add_i32 s24, s24, s20
	v_lshl_add_u64 v[144:145], s[42:43], 0, v[2:3]
	s_mov_b32 m0, s24
	ds_read_b128 v[204:207], v149 offset:16384
	ds_read_b128 v[208:211], v149 offset:17408
	ds_read_b128 v[212:215], v149 offset:18432
	ds_read_b128 v[216:219], v149 offset:19456
	ds_read_b128 v[220:223], v149 offset:20480
	ds_read_b128 v[224:227], v149 offset:21504
	ds_read_b128 v[228:231], v149 offset:22528
	ds_read_b128 v[232:235], v149 offset:23552
	global_load_lds_dwordx4 v[144:145], off
	s_add_i32 m0, s24, 0x2000
	s_add_u32 s38, s42, 0xb0000
	v_lshl_add_u64 v[154:155], s[42:43], 0, v[134:135]
	s_addc_u32 s39, s43, 0
	s_add_i32 s24, s25, s20
	global_load_lds_dwordx4 v[154:155], off
	v_lshl_add_u64 v[192:193], s[38:39], 0, v[2:3]
	s_mov_b32 m0, s24
	v_lshl_add_u64 v[236:237], s[44:45], 0, v[132:133]
	global_load_lds_dwordx4 v[192:193], off
	v_lshl_add_u64 v[192:193], s[38:39], 0, v[134:135]
	s_add_i32 m0, s24, 0x2000
	s_nop 0
	global_load_lds_dwordx4 v[192:193], off
	v_lshl_add_u64 v[192:193], s[44:45], 0, v[0:1]
	s_mov_b32 m0, s21
	s_nop 0
	global_load_lds_dwordx4 v[192:193], off
	s_mov_b32 m0, s22
	s_nop 0
	global_load_lds_dwordx4 v[236:237], off
	s_waitcnt vmcnt(8)
	s_waitcnt lgkmcnt(0)
	s_barrier
	s_setprio 1
	s_waitcnt lgkmcnt(0)
	v_mfma_f32_16x16x32_bf16 v[64:67], v[140:143], v[204:207], v[64:67]
	v_mfma_f32_16x16x32_bf16 v[60:63], v[172:175], v[204:207], v[60:63]
	v_mfma_f32_16x16x32_bf16 v[48:51], v[140:143], v[212:215], v[48:51]
	v_mfma_f32_16x16x32_bf16 v[44:47], v[172:175], v[212:215], v[44:47]
	v_mfma_f32_16x16x32_bf16 v[32:35], v[140:143], v[220:223], v[32:35]
	v_mfma_f32_16x16x32_bf16 v[28:31], v[172:175], v[220:223], v[28:31]
	v_mfma_f32_16x16x32_bf16 v[16:19], v[140:143], v[228:231], v[16:19]
	v_mfma_f32_16x16x32_bf16 v[12:15], v[172:175], v[228:231], v[12:15]
	v_mfma_f32_16x16x32_bf16 v[64:67], v[150:153], v[208:211], v[64:67]
	v_mfma_f32_16x16x32_bf16 v[60:63], v[176:179], v[208:211], v[60:63]
	v_mfma_f32_16x16x32_bf16 v[48:51], v[150:153], v[216:219], v[48:51]
	v_mfma_f32_16x16x32_bf16 v[44:47], v[176:179], v[216:219], v[44:47]
	v_mfma_f32_16x16x32_bf16 v[32:35], v[150:153], v[224:227], v[32:35]
	v_mfma_f32_16x16x32_bf16 v[28:31], v[176:179], v[224:227], v[28:31]
	v_mfma_f32_16x16x32_bf16 v[16:19], v[150:153], v[232:235], v[16:19]
	v_mfma_f32_16x16x32_bf16 v[12:15], v[176:179], v[232:235], v[12:15]
	s_setprio 0
	s_setprio 1
	v_mfma_f32_16x16x32_bf16 v[56:59], v[180:183], v[204:207], v[56:59]
	v_mfma_f32_16x16x32_bf16 v[52:55], v[188:191], v[204:207], v[52:55]
	v_mfma_f32_16x16x32_bf16 v[40:43], v[180:183], v[212:215], v[40:43]
	v_mfma_f32_16x16x32_bf16 v[36:39], v[188:191], v[212:215], v[36:39]
	v_mfma_f32_16x16x32_bf16 v[24:27], v[180:183], v[220:223], v[24:27]
	v_mfma_f32_16x16x32_bf16 v[20:23], v[188:191], v[220:223], v[20:23]
	v_mfma_f32_16x16x32_bf16 v[8:11], v[180:183], v[228:231], v[8:11]
	v_mfma_f32_16x16x32_bf16 v[4:7], v[188:191], v[228:231], v[4:7]
	v_mfma_f32_16x16x32_bf16 v[56:59], v[184:187], v[208:211], v[56:59]
	v_mfma_f32_16x16x32_bf16 v[52:55], v[200:203], v[208:211], v[52:55]
	v_mfma_f32_16x16x32_bf16 v[40:43], v[184:187], v[216:219], v[40:43]
	v_mfma_f32_16x16x32_bf16 v[36:39], v[200:203], v[216:219], v[36:39]
	v_mfma_f32_16x16x32_bf16 v[24:27], v[184:187], v[224:227], v[24:27]
	v_mfma_f32_16x16x32_bf16 v[20:23], v[200:203], v[224:227], v[20:23]
	v_mfma_f32_16x16x32_bf16 v[8:11], v[184:187], v[232:235], v[8:11]
	v_mfma_f32_16x16x32_bf16 v[4:7], v[200:203], v[232:235], v[4:7]
	s_setprio 0
	s_barrier
	s_add_i32 s24, 0, 0x18000
	s_add_i32 s25, 0, 0x1c000
	v_add_u32_e32 v176, s24, v147
	v_add_u32_e32 v199, s25, v147
	ds_read_b128 v[140:143], v176
	ds_read_b128 v[150:153], v176 offset:1024
	ds_read_b128 v[172:175], v176 offset:2048
	ds_read_b128 v[176:179], v176 offset:3072
	ds_read_b128 v[180:183], v199
	ds_read_b128 v[184:187], v199 offset:1024
	ds_read_b128 v[188:191], v199 offset:2048
	ds_read_b128 v[200:203], v199 offset:3072
	s_add_u32 s38, s44, 0xb0000
	s_addc_u32 s39, s45, 0
	s_mov_b32 m0, s23
	v_lshl_add_u64 v[238:239], s[38:39], 0, v[0:1]
	ds_read_b128 v[204:207], v149 offset:32768
	ds_read_b128 v[208:211], v149 offset:33792
	ds_read_b128 v[212:215], v149 offset:34816
	ds_read_b128 v[216:219], v149 offset:35840
	ds_read_b128 v[220:223], v149 offset:36864
	ds_read_b128 v[224:227], v149 offset:37888
	ds_read_b128 v[228:231], v149 offset:38912
	ds_read_b128 v[232:235], v149 offset:39936
	global_load_lds_dwordx4 v[238:239], off
	v_lshl_add_u64 v[238:239], s[38:39], 0, v[132:133]
	s_mov_b32 m0, s36
	s_nop 0
	global_load_lds_dwordx4 v[238:239], off
	s_waitcnt vmcnt(8)
	s_waitcnt lgkmcnt(0)
	s_barrier
	s_setprio 1
	s_waitcnt lgkmcnt(0)
	v_mfma_f32_16x16x32_bf16 v[128:131], v[140:143], v[204:207], v[128:131]
	v_mfma_f32_16x16x32_bf16 v[124:127], v[172:175], v[204:207], v[124:127]
	v_mfma_f32_16x16x32_bf16 v[112:115], v[140:143], v[212:215], v[112:115]
	v_mfma_f32_16x16x32_bf16 v[108:111], v[172:175], v[212:215], v[108:111]
	v_mfma_f32_16x16x32_bf16 v[96:99], v[140:143], v[220:223], v[96:99]
	v_mfma_f32_16x16x32_bf16 v[92:95], v[172:175], v[220:223], v[92:95]
	v_mfma_f32_16x16x32_bf16 v[80:83], v[140:143], v[228:231], v[80:83]
	v_mfma_f32_16x16x32_bf16 v[76:79], v[172:175], v[228:231], v[76:79]
	v_mfma_f32_16x16x32_bf16 v[128:131], v[150:153], v[208:211], v[128:131]
	v_mfma_f32_16x16x32_bf16 v[124:127], v[176:179], v[208:211], v[124:127]
	v_mfma_f32_16x16x32_bf16 v[112:115], v[150:153], v[216:219], v[112:115]
	v_mfma_f32_16x16x32_bf16 v[108:111], v[176:179], v[216:219], v[108:111]
	v_mfma_f32_16x16x32_bf16 v[96:99], v[150:153], v[224:227], v[96:99]
	v_mfma_f32_16x16x32_bf16 v[92:95], v[176:179], v[224:227], v[92:95]
	v_mfma_f32_16x16x32_bf16 v[80:83], v[150:153], v[232:235], v[80:83]
	v_mfma_f32_16x16x32_bf16 v[76:79], v[176:179], v[232:235], v[76:79]
	s_setprio 0
	s_setprio 1
	v_mfma_f32_16x16x32_bf16 v[120:123], v[180:183], v[204:207], v[120:123]
	v_mfma_f32_16x16x32_bf16 v[116:119], v[188:191], v[204:207], v[116:119]
	v_mfma_f32_16x16x32_bf16 v[104:107], v[180:183], v[212:215], v[104:107]
	v_mfma_f32_16x16x32_bf16 v[100:103], v[188:191], v[212:215], v[100:103]
	v_mfma_f32_16x16x32_bf16 v[88:91], v[180:183], v[220:223], v[88:91]
	v_mfma_f32_16x16x32_bf16 v[84:87], v[188:191], v[220:223], v[84:87]
	v_mfma_f32_16x16x32_bf16 v[72:75], v[180:183], v[228:231], v[72:75]
	v_mfma_f32_16x16x32_bf16 v[68:71], v[188:191], v[228:231], v[68:71]
	v_mfma_f32_16x16x32_bf16 v[120:123], v[184:187], v[208:211], v[120:123]
	v_mfma_f32_16x16x32_bf16 v[116:119], v[200:203], v[208:211], v[116:119]
	v_mfma_f32_16x16x32_bf16 v[104:107], v[184:187], v[216:219], v[104:107]
	v_mfma_f32_16x16x32_bf16 v[100:103], v[200:203], v[216:219], v[100:103]
	v_mfma_f32_16x16x32_bf16 v[88:91], v[184:187], v[224:227], v[88:91]
	v_mfma_f32_16x16x32_bf16 v[84:87], v[200:203], v[224:227], v[84:87]
	v_mfma_f32_16x16x32_bf16 v[72:75], v[184:187], v[232:235], v[72:75]
	v_mfma_f32_16x16x32_bf16 v[68:71], v[200:203], v[232:235], v[68:71]
	s_setprio 0
	s_barrier
	s_add_i32 s24, s24, s20
	v_lshl_add_u64 v[144:145], v[144:145], 0, s[26:27]
	s_mov_b32 m0, s24
	ds_read_b128 v[204:207], v149 offset:49152
	ds_read_b128 v[208:211], v149 offset:50176
	ds_read_b128 v[212:215], v149 offset:51200
	ds_read_b128 v[216:219], v149 offset:52224
	ds_read_b128 v[220:223], v149 offset:53248
	ds_read_b128 v[224:227], v149 offset:54272
	ds_read_b128 v[228:231], v149 offset:55296
	ds_read_b128 v[232:235], v149 offset:56320
	global_load_lds_dwordx4 v[144:145], off
	s_add_i32 m0, s24, 0x2000
	s_add_u32 s38, s42, 0xb0080
	v_lshl_add_u64 v[144:145], v[154:155], 0, s[26:27]
	s_addc_u32 s39, s43, 0
	s_add_i32 s24, s25, s20
	global_load_lds_dwordx4 v[144:145], off
	v_lshl_add_u64 v[144:145], s[38:39], 0, v[2:3]
	s_mov_b32 m0, s24
	s_nop 0
	global_load_lds_dwordx4 v[144:145], off
	v_lshl_add_u64 v[144:145], s[38:39], 0, v[134:135]
	s_add_i32 m0, s24, 0x2000
	s_nop 0
	global_load_lds_dwordx4 v[144:145], off
	v_lshl_add_u64 v[144:145], v[192:193], 0, s[26:27]
	s_mov_b32 m0, s46
	s_nop 0
	global_load_lds_dwordx4 v[144:145], off
	v_lshl_add_u64 v[144:145], v[236:237], 0, s[26:27]
	s_mov_b32 m0, s47
	s_nop 0
	global_load_lds_dwordx4 v[144:145], off
	s_waitcnt vmcnt(8)
	s_waitcnt lgkmcnt(0)
	s_barrier
	s_setprio 1
	s_waitcnt lgkmcnt(0)
	v_mfma_f32_16x16x32_bf16 v[64:67], v[140:143], v[204:207], v[64:67]
	v_mfma_f32_16x16x32_bf16 v[60:63], v[172:175], v[204:207], v[60:63]
	v_mfma_f32_16x16x32_bf16 v[48:51], v[140:143], v[212:215], v[48:51]
	v_mfma_f32_16x16x32_bf16 v[44:47], v[172:175], v[212:215], v[44:47]
	v_mfma_f32_16x16x32_bf16 v[32:35], v[140:143], v[220:223], v[32:35]
	v_mfma_f32_16x16x32_bf16 v[28:31], v[172:175], v[220:223], v[28:31]
	v_mfma_f32_16x16x32_bf16 v[16:19], v[140:143], v[228:231], v[16:19]
	v_mfma_f32_16x16x32_bf16 v[12:15], v[172:175], v[228:231], v[12:15]
	v_mfma_f32_16x16x32_bf16 v[64:67], v[150:153], v[208:211], v[64:67]
	v_mfma_f32_16x16x32_bf16 v[60:63], v[176:179], v[208:211], v[60:63]
	v_mfma_f32_16x16x32_bf16 v[48:51], v[150:153], v[216:219], v[48:51]
	v_mfma_f32_16x16x32_bf16 v[44:47], v[176:179], v[216:219], v[44:47]
	v_mfma_f32_16x16x32_bf16 v[32:35], v[150:153], v[224:227], v[32:35]
	v_mfma_f32_16x16x32_bf16 v[28:31], v[176:179], v[224:227], v[28:31]
	v_mfma_f32_16x16x32_bf16 v[16:19], v[150:153], v[232:235], v[16:19]
	v_mfma_f32_16x16x32_bf16 v[12:15], v[176:179], v[232:235], v[12:15]
	s_setprio 0
	s_setprio 1
	v_mfma_f32_16x16x32_bf16 v[56:59], v[180:183], v[204:207], v[56:59]
	v_mfma_f32_16x16x32_bf16 v[52:55], v[188:191], v[204:207], v[52:55]
	v_mfma_f32_16x16x32_bf16 v[40:43], v[180:183], v[212:215], v[40:43]
	v_mfma_f32_16x16x32_bf16 v[36:39], v[188:191], v[212:215], v[36:39]
	v_mfma_f32_16x16x32_bf16 v[24:27], v[180:183], v[220:223], v[24:27]
	v_mfma_f32_16x16x32_bf16 v[20:23], v[188:191], v[220:223], v[20:23]
	v_mfma_f32_16x16x32_bf16 v[8:11], v[180:183], v[228:231], v[8:11]
	v_mfma_f32_16x16x32_bf16 v[4:7], v[188:191], v[228:231], v[4:7]
	v_mfma_f32_16x16x32_bf16 v[56:59], v[184:187], v[208:211], v[56:59]
	v_mfma_f32_16x16x32_bf16 v[52:55], v[200:203], v[208:211], v[52:55]
	v_mfma_f32_16x16x32_bf16 v[40:43], v[184:187], v[216:219], v[40:43]
	v_mfma_f32_16x16x32_bf16 v[36:39], v[200:203], v[216:219], v[36:39]
	v_mfma_f32_16x16x32_bf16 v[24:27], v[184:187], v[224:227], v[24:27]
	v_mfma_f32_16x16x32_bf16 v[20:23], v[200:203], v[224:227], v[20:23]
	v_mfma_f32_16x16x32_bf16 v[8:11], v[184:187], v[232:235], v[8:11]
	v_mfma_f32_16x16x32_bf16 v[4:7], v[200:203], v[232:235], v[4:7]
	s_setprio 0
	s_barrier
	s_add_i32 s61, s61, 2
	s_add_u32 s55, s55, 0x100
	s_addc_u32 s60, s60, 0
	s_cmp_gt_u32 s61, 41
	s_mov_b64 s[38:39], s[14:15]
	s_cbranch_scc0 .LBB0_1044
	s_and_b64 vcc, exec, s[10:11]
	s_cbranch_vccz .LBB0_1047
	s_barrier

	.amdhsa_kernel _Z14fwd_megakernel4Args
		.amdhsa_group_segment_fixed_size 0
		.amdhsa_private_segment_fixed_size 0
		.amdhsa_kernarg_size 416
		.amdhsa_user_sgpr_count 2
		.amdhsa_user_sgpr_dispatch_ptr 0
		.amdhsa_user_sgpr_queue_ptr 0
		.amdhsa_user_sgpr_kernarg_segment_ptr 1
		.amdhsa_user_sgpr_dispatch_id 0
		.amdhsa_user_sgpr_kernarg_preload_length 0
		.amdhsa_user_sgpr_kernarg_preload_offset 0
		.amdhsa_user_sgpr_private_segment_size 0
		.amdhsa_uses_dynamic_stack 0
		.amdhsa_enable_private_segment 0
		.amdhsa_system_sgpr_workgroup_id_x 1
		.amdhsa_system_sgpr_workgroup_id_y 0
		.amdhsa_system_sgpr_workgroup_id_z 0
		.amdhsa_system_sgpr_workgroup_info 0
		.amdhsa_system_vgpr_workitem_id 2
		.amdhsa_next_free_vgpr 250
		.amdhsa_next_free_sgpr 102
		.amdhsa_accum_offset 252
		.amdhsa_reserve_vcc 1
		.amdhsa_float_round_mode_32 0
		.amdhsa_float_round_mode_16_64 0
		.amdhsa_float_denorm_mode_32 3
		.amdhsa_float_denorm_mode_16_64 3
		.amdhsa_dx10_clamp 1
		.amdhsa_ieee_mode 1
		.amdhsa_fp16_overflow 0
		.amdhsa_tg_split 0
		.amdhsa_exception_fp_ieee_invalid_op 0
		.amdhsa_exception_fp_denorm_src 0
		.amdhsa_exception_fp_ieee_div_zero 0
		.amdhsa_exception_fp_ieee_overflow 0
		.amdhsa_exception_fp_ieee_underflow 0
		.amdhsa_exception_fp_ieee_inexact 0
		.amdhsa_exception_int_div_zero 0
	.end_amdhsa_kernel

.Lfunc_end0:
	.size	_Z14fwd_megakernel4Args, .Lfunc_end0-_Z14fwd_megakernel4Args
	.set _Z14fwd_megakernel4Args.num_vgpr, 250
	.set _Z14fwd_megakernel4Args.num_agpr, 0
	.set _Z14fwd_megakernel4Args.numbered_sgpr, 102
	.set _Z14fwd_megakernel4Args.num_named_barrier, 0
	.set _Z14fwd_megakernel4Args.private_seg_size, 0
	.set _Z14fwd_megakernel4Args.uses_vcc, 1
	.set _Z14fwd_megakernel4Args.uses_flat_scratch, 0
	.set _Z14fwd_megakernel4Args.has_dyn_sized_stack, 0
	.set _Z14fwd_megakernel4Args.has_recursion, 0
	.set _Z14fwd_megakernel4Args.has_indirect_call, 0

amdhsa.kernels:
  - .agpr_count:     0
    .args:
      - .offset:         0
        .size:           160
        .value_kind:     by_value
      - .offset:         160
        .size:           4
        .value_kind:     hidden_block_count_x
      - .offset:         164
        .size:           4
        .value_kind:     hidden_block_count_y
      - .offset:         168
        .size:           4
        .value_kind:     hidden_block_count_z
      - .offset:         172
        .size:           2
        .value_kind:     hidden_group_size_x
      - .offset:         174
        .size:           2
        .value_kind:     hidden_group_size_y
      - .offset:         176
        .size:           2
        .value_kind:     hidden_group_size_z
      - .offset:         178
        .size:           2
        .value_kind:     hidden_remainder_x
      - .offset:         180
        .size:           2
        .value_kind:     hidden_remainder_y
      - .offset:         182
        .size:           2
        .value_kind:     hidden_remainder_z
      - .offset:         200
        .size:           8
        .value_kind:     hidden_global_offset_x
      - .offset:         208
        .size:           8
        .value_kind:     hidden_global_offset_y
      - .offset:         216
        .size:           8
        .value_kind:     hidden_global_offset_z
      - .offset:         224
        .size:           2
        .value_kind:     hidden_grid_dims
      - .offset:         248
        .size:           8
        .value_kind:     hidden_multigrid_sync_arg
      - .offset:         280
        .size:           4
        .value_kind:     hidden_dynamic_lds_size
    .group_segment_fixed_size: 0
    .kernarg_segment_align: 8
    .kernarg_segment_size: 416
    .language:       OpenCL C
    .language_version:
      - 2
      - 0
    .max_flat_workgroup_size: 512
    .name:           _Z14fwd_megakernel4Args
    .private_segment_fixed_size: 0
    .sgpr_count:     108
    .sgpr_spill_count: 272
    .symbol:         _Z14fwd_megakernel4Args.kd
    .uniform_work_group_size: 1
    .uses_dynamic_stack: false
    .vgpr_count:     250
    .vgpr_spill_count: 0
    .wavefront_size: 64
